# post phase row loop: norm-gain and S5-part loads (12) issued with the first load group; on top of row pass A/B/C load hoists
# baseline (speedup 1.0000x reference)
; __device__ __forceinline__ float siluf_(float x) { return x / (1.f + __expf(-x)); }
; __device__ __forceinline__ void post_phase(const Args& a, int l, int nrows) {
;     ...
;         float v[2][8]; float ss = 0.f;
; #pragma unroll
;         for (int k = 0; k < 2; ++k) { const int ch = 8 * lane + 512 * k; const float dd = dssd[ch >> 6];
;             const u32x4 zw = *(const u32x4*)(P + (size_t)row * NINP + ZOFF + ch); float z[8]; unpack8(zw, z);
;             float yf[8], yb[8]; unpack8(*(const u32x4*)(yssd + (size_t)row * 1024 + ch), yf); unpack8(*(const u32x4*)(yssd + ((size_t)MROWS + row) * 1024 + ch), yb);
; #pragma unroll
;             for (int q = 0; q < 2; ++q) { const f32x4 xv = *(const f32x4*)(xbc + (size_t)row * 1536 + ch + 4 * q);
; #pragma unroll
;                 for (int j = 0; j < 4; ++j) { const float y = (yf[4 * q + j] + yb[4 * q + j] + dd * xv[j]) * siluf_(z[4 * q + j]); v[k][4 * q + j] = y; ss += y * y; } } }
.LBB0_622:
	v_lshl_add_u64 v[48:49], s[86:87], 0, v[46:47]
	v_add_co_u32_e32 v2, vcc, 0x8d01000, v48
	v_lshl_add_u64 v[50:51], s[86:87], 0, v[42:43]
	s_nop 0
	v_addc_co_u32_e32 v3, vcc, 0, v49, vcc
	v_add_co_u32_e32 v4, vcc, 0x23a00000, v50
	global_load_dwordx4 v[28:31], v[2:3], off offset:2048
	s_nop 0
	v_addc_co_u32_e32 v5, vcc, 0, v51, vcc
	v_add_co_u32_e32 v6, vcc, 0x24b00000, v50
	global_load_dwordx4 v[62:65], v[4:5], off
	s_nop 0
	v_addc_co_u32_e32 v7, vcc, 0, v51, vcc
	global_load_dwordx4 v[66:69], v[6:7], off
	global_load_dword v54, v[34:35], off
	v_lshl_add_u64 v[8:9], s[86:87], 0, v[44:45]
	v_add_co_u32_e32 v24, vcc, 0x20700000, v8
	s_mov_b64 s[6:7], 0x20700000
	s_nop 0
	v_addc_co_u32_e32 v25, vcc, 0, v9, vcc
	v_lshl_add_u64 v[10:11], v[8:9], 0, s[6:7]
	global_load_dwordx4 v[70:73], v[24:25], off
	global_load_dwordx4 v[74:77], v[10:11], off offset:16
	global_load_dword v0, v[36:37], off
	global_load_dwordx4 v[20:23], v[2:3], off offset:3072
	global_load_dwordx4 v[16:19], v[4:5], off offset:1024
	global_load_dwordx4 v[12:15], v[6:7], off offset:1024
	s_mov_b64 s[6:7], 0x20700800
	v_lshl_add_u64 v[2:3], v[8:9], 0, s[6:7]
	global_load_dwordx4 v[24:27], v[24:25], off offset:2048
	s_nop 0
	global_load_dwordx4 v[78:81], v[2:3], off offset:16
	global_load_dwordx4 v[4:7], v[38:39], off offset:16
	global_load_dwordx4 v[8:11], v[38:39], off
	s_mov_b64 s[6:7], 0x8d02000
	v_lshl_add_u64 v[84:85], v[48:49], 0, s[6:7]
	s_mov_b64 s[6:7], 0x8d03000
	v_lshl_add_u64 v[86:87], v[48:49], 0, s[6:7]
	s_mov_b64 s[6:7], 0x27e00000
	v_lshl_add_u64 v[136:137], v[50:51], 0, s[6:7]
	s_mov_b64 s[6:7], 0x28f00000
	v_lshl_add_u64 v[138:139], v[50:51], 0, s[6:7]
	global_load_dwordx4 v[88:91], v[38:39], off offset:2064
	global_load_dwordx4 v[92:95], v[38:39], off offset:2048
	global_load_dwordx4 v[96:99], v[84:85], off offset:3136
	global_load_dwordx4 v[100:103], v[136:137], off
	global_load_dwordx4 v[104:107], v[138:139], off
	global_load_dwordx4 v[108:111], v[40:41], off offset:16
	global_load_dwordx4 v[112:115], v[40:41], off
	global_load_dwordx4 v[116:119], v[86:87], off offset:64
	global_load_dwordx4 v[120:123], v[136:137], off offset:1024
	global_load_dwordx4 v[124:127], v[138:139], off offset:1024
	global_load_dwordx4 v[128:131], v[40:41], off offset:2064
	global_load_dwordx4 v[132:135], v[40:41], off offset:2048
	v_add_u32_e32 v32, s44, v32
	v_lshl_add_u64 v[42:43], v[42:43], 0, s[60:61]
	v_lshl_add_u64 v[44:45], v[44:45], 0, s[10:11]
	v_lshl_add_u64 v[46:47], v[46:47], 0, s[14:15]
	s_waitcnt vmcnt(25)
	v_lshlrev_b32_e32 v33, 16, v31
	v_and_b32_e32 v31, 0xffff0000, v31
	v_mul_f32_e32 v61, 0xbfb8aa3b, v33
	v_exp_f32_e32 v82, v61
	s_waitcnt vmcnt(24)
	v_lshlrev_b32_e32 v2, 16, v65
	v_and_b32_e32 v3, 0xffff0000, v65
	s_waitcnt vmcnt(23)
	v_lshlrev_b32_e32 v52, 16, v69
	v_and_b32_e32 v53, 0xffff0000, v69
	v_pk_add_f32 v[2:3], v[2:3], v[52:53]
	v_mul_f32_e32 v52, 0xbfb8aa3b, v31
	v_exp_f32_e32 v83, v52
	s_waitcnt vmcnt(20)
	v_pk_fma_f32 v[2:3], v[54:55], v[76:77], v[2:3] op_sel_hi:[0,1,1]
	v_pk_add_f32 v[52:53], v[82:83], 1.0 op_sel_hi:[1,0]
	s_nop 0
	v_div_scale_f32 v61, s[6:7], v53, v53, v31
	v_rcp_f32_e32 v65, v61
	s_nop 0
	v_fma_f32 v69, -v61, v65, 1.0
	v_fmac_f32_e32 v65, v69, v65
	v_div_scale_f32 v69, vcc, v31, v53, v31
	v_mul_f32_e32 v76, v69, v65
	v_fma_f32 v77, -v61, v76, v69
	v_fmac_f32_e32 v76, v77, v65
	v_fma_f32 v61, -v61, v76, v69
	v_div_fmas_f32 v61, v61, v65, v76
	v_div_fixup_f32 v53, v61, v53, v31
	v_div_scale_f32 v31, s[6:7], v52, v52, v33
	v_rcp_f32_e32 v61, v31
	s_nop 0
	v_fma_f32 v65, -v31, v61, 1.0
	v_fmac_f32_e32 v61, v65, v61
	v_div_scale_f32 v65, vcc, v33, v52, v33
	v_mul_f32_e32 v69, v65, v61
	v_fma_f32 v76, -v31, v69, v65
	v_fmac_f32_e32 v69, v76, v61
	v_fma_f32 v31, -v31, v69, v65
	v_div_fmas_f32 v31, v31, v61, v69
	v_div_fixup_f32 v52, v31, v52, v33
	v_lshlrev_b32_e32 v33, 16, v30
	v_and_b32_e32 v61, 0xffff0000, v30
	v_lshlrev_b32_e32 v30, 16, v64
	v_and_b32_e32 v31, 0xffff0000, v64
	v_lshlrev_b32_e32 v64, 16, v68
	v_and_b32_e32 v65, 0xffff0000, v68
	v_mul_f32_e32 v68, 0xbfb8aa3b, v33
	v_pk_add_f32 v[30:31], v[30:31], v[64:65]
	v_mul_f32_e32 v64, 0xbfb8aa3b, v61
	v_exp_f32_e32 v68, v68
	v_exp_f32_e32 v69, v64
	v_pk_fma_f32 v[30:31], v[54:55], v[74:75], v[30:31] op_sel_hi:[0,1,1]
	v_pk_mul_f32 v[52:53], v[2:3], v[52:53]
	v_pk_add_f32 v[64:65], v[68:69], 1.0 op_sel_hi:[1,0]
	s_nop 0
	v_div_scale_f32 v68, s[6:7], v65, v65, v61
	v_rcp_f32_e32 v69, v68
	v_pk_mul_f32 v[2:3], v[52:53], v[52:53]
	v_fma_f32 v74, -v68, v69, 1.0
	v_fmac_f32_e32 v69, v74, v69
	v_div_scale_f32 v74, vcc, v61, v65, v61
	v_mul_f32_e32 v75, v74, v69
	v_fma_f32 v76, -v68, v75, v74
	v_fmac_f32_e32 v75, v76, v69
	v_fma_f32 v68, -v68, v75, v74
	v_div_fmas_f32 v68, v68, v69, v75
	v_div_fixup_f32 v65, v68, v65, v61
	v_div_scale_f32 v61, s[6:7], v64, v64, v33
	v_rcp_f32_e32 v68, v61
	s_nop 0
	v_fma_f32 v69, -v61, v68, 1.0
	v_fmac_f32_e32 v68, v69, v68
	v_div_scale_f32 v69, vcc, v33, v64, v33
	v_mul_f32_e32 v74, v69, v68
	v_fma_f32 v75, -v61, v74, v69
	v_fmac_f32_e32 v74, v75, v68
	v_fma_f32 v61, -v61, v74, v69
	v_div_fmas_f32 v61, v61, v68, v74
	v_div_fixup_f32 v64, v61, v64, v33
	v_lshlrev_b32_e32 v33, 16, v29
	v_and_b32_e32 v29, 0xffff0000, v29
	v_mul_f32_e32 v61, 0xbfb8aa3b, v33
	v_exp_f32_e32 v76, v61
	v_mul_f32_e32 v61, 0xbfb8aa3b, v29
	v_exp_f32_e32 v77, v61
	v_lshlrev_b32_e32 v68, 16, v63
	v_and_b32_e32 v69, 0xffff0000, v63
	v_lshlrev_b32_e32 v74, 16, v67
	v_and_b32_e32 v75, 0xffff0000, v67
	v_pk_add_f32 v[68:69], v[68:69], v[74:75]
	v_pk_mul_f32 v[30:31], v[30:31], v[64:65]
	v_pk_fma_f32 v[68:69], v[54:55], v[72:73], v[68:69] op_sel_hi:[0,1,1]
; __device__ __forceinline__ float siluf_(float x) { return x / (1.f + __expf(-x)); }
; __device__ __forceinline__ void post_phase(const Args& a, int l, int nrows) {
;     ...
;         for (int k = 0; k < 2; ++k) { const int ch = 8 * lane + 512 * k; const float dd = dssd[ch >> 6];
;             const u32x4 zw = *(const u32x4*)(P + (size_t)row * NINP + ZOFF + ch); float z[8]; unpack8(zw, z);
;             float yf[8], yb[8]; unpack8(*(const u32x4*)(yssd + (size_t)row * 1024 + ch), yf); unpack8(*(const u32x4*)(yssd + ((size_t)MROWS + row) * 1024 + ch), yb);
; #pragma unroll
;             for (int q = 0; q < 2; ++q) { const f32x4 xv = *(const f32x4*)(xbc + (size_t)row * 1536 + ch + 4 * q);
; #pragma unroll
;                 for (int j = 0; j < 4; ++j) { const float y = (yf[4 * q + j] + yb[4 * q + j] + dd * xv[j]) * siluf_(z[4 * q + j]); v[k][4 * q + j] = y; ss += y * y; } } }
	v_pk_add_f32 v[72:73], v[76:77], 1.0 op_sel_hi:[1,0]
	v_pk_mul_f32 v[64:65], v[30:31], v[30:31]
	v_div_scale_f32 v61, s[6:7], v73, v73, v29
	v_rcp_f32_e32 v63, v61
	s_nop 0
	v_fma_f32 v67, -v61, v63, 1.0
	v_fmac_f32_e32 v63, v67, v63
	v_div_scale_f32 v67, vcc, v29, v73, v29
	v_mul_f32_e32 v74, v67, v63
	v_fma_f32 v75, -v61, v74, v67
	v_fmac_f32_e32 v74, v75, v63
	v_fma_f32 v61, -v61, v74, v67
	v_div_fmas_f32 v61, v61, v63, v74
	v_div_fixup_f32 v73, v61, v73, v29
	v_div_scale_f32 v29, s[6:7], v72, v72, v33
	v_rcp_f32_e32 v61, v29
	s_nop 0
	v_fma_f32 v63, -v29, v61, 1.0
	v_fmac_f32_e32 v61, v63, v61
	v_div_scale_f32 v63, vcc, v33, v72, v33
	v_mul_f32_e32 v67, v63, v61
	v_fma_f32 v74, -v29, v67, v63
	v_fmac_f32_e32 v67, v74, v61
	v_fma_f32 v29, -v29, v67, v63
	v_div_fmas_f32 v29, v29, v61, v67
	v_div_fixup_f32 v72, v29, v72, v33
	v_lshlrev_b32_e32 v33, 16, v28
	v_and_b32_e32 v61, 0xffff0000, v28
	v_lshlrev_b32_e32 v28, 16, v62
	v_and_b32_e32 v29, 0xffff0000, v62
	v_lshlrev_b32_e32 v62, 16, v66
	v_and_b32_e32 v63, 0xffff0000, v66
	v_pk_add_f32 v[28:29], v[28:29], v[62:63]
	v_mul_f32_e32 v66, 0xbfb8aa3b, v33
	v_pk_fma_f32 v[28:29], v[54:55], v[70:71], v[28:29] op_sel_hi:[0,1,1]
	v_mul_f32_e32 v54, 0xbfb8aa3b, v61
	v_exp_f32_e32 v66, v66
	v_exp_f32_e32 v67, v54
	v_pk_mul_f32 v[68:69], v[68:69], v[72:73]
	v_pk_add_f32 v[62:63], v[66:67], 1.0 op_sel_hi:[1,0]
	s_nop 0
	v_div_scale_f32 v54, s[6:7], v63, v63, v61
	v_rcp_f32_e32 v66, v54
	v_pk_mul_f32 v[72:73], v[68:69], v[68:69]
	v_fma_f32 v67, -v54, v66, 1.0
	v_fmac_f32_e32 v66, v67, v66
	v_div_scale_f32 v67, vcc, v61, v63, v61
	v_mul_f32_e32 v70, v67, v66
	v_fma_f32 v71, -v54, v70, v67
	v_fmac_f32_e32 v70, v71, v66
	v_fma_f32 v54, -v54, v70, v67
	v_div_fmas_f32 v54, v54, v66, v70
	v_div_fixup_f32 v63, v54, v63, v61
	v_div_scale_f32 v54, s[6:7], v62, v62, v33
	v_rcp_f32_e32 v61, v54
	s_waitcnt vmcnt(16)
	v_and_b32_e32 v71, 0xffff0000, v15
	v_fma_f32 v66, -v54, v61, 1.0
	v_fmac_f32_e32 v61, v66, v61
	v_div_scale_f32 v66, vcc, v33, v62, v33
	v_mul_f32_e32 v67, v66, v61
	v_fma_f32 v70, -v54, v67, v66
	v_fmac_f32_e32 v67, v70, v61
	v_fma_f32 v54, -v54, v67, v66
	v_div_fmas_f32 v54, v54, v61, v67
	v_div_fixup_f32 v62, v54, v62, v33
	v_lshlrev_b32_e32 v33, 16, v23
	v_and_b32_e32 v23, 0xffff0000, v23
	v_lshlrev_b32_e32 v70, 16, v15
	v_mul_f32_e32 v15, 0xbfb8aa3b, v33
	v_exp_f32_e32 v74, v15
	v_mul_f32_e32 v15, 0xbfb8aa3b, v23
	v_exp_f32_e32 v75, v15
	v_pk_mul_f32 v[62:63], v[28:29], v[62:63]
	v_lshlrev_b32_e32 v28, 16, v19
	v_and_b32_e32 v29, 0xffff0000, v19
	v_pk_add_f32 v[28:29], v[28:29], v[70:71]
	v_pk_add_f32 v[70:71], v[74:75], 1.0 op_sel_hi:[1,0]
	s_waitcnt vmcnt(14)
	v_pk_fma_f32 v[28:29], v[0:1], v[80:81], v[28:29] op_sel_hi:[0,1,1]
	v_div_scale_f32 v15, s[6:7], v71, v71, v23
	v_rcp_f32_e32 v19, v15
	v_pk_mul_f32 v[66:67], v[62:63], v[62:63]
	v_fma_f32 v54, -v15, v19, 1.0
	v_fmac_f32_e32 v19, v54, v19
	v_div_scale_f32 v54, vcc, v23, v71, v23
	v_mul_f32_e32 v61, v54, v19
	v_fma_f32 v74, -v15, v61, v54
	v_fmac_f32_e32 v61, v74, v19
	v_fma_f32 v15, -v15, v61, v54
	v_div_fmas_f32 v15, v15, v19, v61
	v_div_fixup_f32 v71, v15, v71, v23
	v_div_scale_f32 v15, s[6:7], v70, v70, v33
	v_rcp_f32_e32 v19, v15
	s_nop 0
	v_fma_f32 v23, -v15, v19, 1.0
	v_fmac_f32_e32 v19, v23, v19
	v_div_scale_f32 v23, vcc, v33, v70, v33
	v_mul_f32_e32 v54, v23, v19
	v_fma_f32 v61, -v15, v54, v23
	v_fmac_f32_e32 v54, v61, v19
	v_fma_f32 v15, -v15, v54, v23
	v_div_fmas_f32 v15, v15, v19, v54
	v_div_fixup_f32 v70, v15, v70, v33
	v_lshlrev_b32_e32 v33, 16, v22
	v_and_b32_e32 v54, 0xffff0000, v22
	v_lshlrev_b32_e32 v22, 16, v18
	v_and_b32_e32 v23, 0xffff0000, v18
	v_lshlrev_b32_e32 v18, 16, v14
	v_and_b32_e32 v19, 0xffff0000, v14
	v_mul_f32_e32 v14, 0xbfb8aa3b, v33
	v_mul_f32_e32 v15, 0xbfb8aa3b, v54
	v_exp_f32_e32 v14, v14
	v_exp_f32_e32 v15, v15
	v_pk_add_f32 v[18:19], v[22:23], v[18:19]
	v_pk_mul_f32 v[28:29], v[28:29], v[70:71]
	v_pk_fma_f32 v[18:19], v[0:1], v[78:79], v[18:19] op_sel_hi:[0,1,1]
	v_pk_add_f32 v[14:15], v[14:15], 1.0 op_sel_hi:[1,0]
	v_pk_mul_f32 v[70:71], v[28:29], v[28:29]
	v_div_scale_f32 v22, s[6:7], v15, v15, v54
	v_rcp_f32_e32 v23, v22
	s_nop 0
	v_fma_f32 v61, -v22, v23, 1.0
	v_fmac_f32_e32 v23, v61, v23
	v_div_scale_f32 v61, vcc, v54, v15, v54
	v_mul_f32_e32 v74, v61, v23
	v_fma_f32 v75, -v22, v74, v61
	v_fmac_f32_e32 v74, v75, v23
	v_fma_f32 v22, -v22, v74, v61
	v_div_fmas_f32 v22, v22, v23, v74
	v_div_fixup_f32 v15, v22, v15, v54
	v_div_scale_f32 v22, s[6:7], v14, v14, v33
	v_rcp_f32_e32 v23, v22
	v_and_b32_e32 v75, 0xffff0000, v13
	v_fma_f32 v54, -v22, v23, 1.0
	v_fmac_f32_e32 v23, v54, v23
	v_div_scale_f32 v54, vcc, v33, v14, v33
	v_mul_f32_e32 v61, v54, v23
	v_fma_f32 v74, -v22, v61, v54
	v_fmac_f32_e32 v61, v74, v23
	v_fma_f32 v22, -v22, v61, v54
	v_div_fmas_f32 v22, v22, v23, v61
	v_div_fixup_f32 v14, v22, v14, v33
	v_lshlrev_b32_e32 v33, 16, v21
	v_and_b32_e32 v21, 0xffff0000, v21
	v_lshlrev_b32_e32 v74, 16, v13
	v_mul_f32_e32 v13, 0xbfb8aa3b, v33
	v_exp_f32_e32 v76, v13
	v_mul_f32_e32 v13, 0xbfb8aa3b, v21
	v_exp_f32_e32 v77, v13
	v_pk_mul_f32 v[14:15], v[18:19], v[14:15]
	v_lshlrev_b32_e32 v18, 16, v17
	v_and_b32_e32 v19, 0xffff0000, v17
	v_pk_add_f32 v[18:19], v[18:19], v[74:75]
	v_pk_mul_f32 v[22:23], v[14:15], v[14:15]
	v_pk_fma_f32 v[18:19], v[0:1], v[26:27], v[18:19] op_sel_hi:[0,1,1]
	v_pk_add_f32 v[26:27], v[76:77], 1.0 op_sel_hi:[1,0]
	s_nop 0
	v_div_scale_f32 v13, s[6:7], v27, v27, v21
	v_rcp_f32_e32 v17, v13
	s_nop 0
	v_fma_f32 v54, -v13, v17, 1.0
	v_fmac_f32_e32 v17, v54, v17
	v_div_scale_f32 v54, vcc, v21, v27, v21
	v_mul_f32_e32 v61, v54, v17
	v_fma_f32 v74, -v13, v61, v54
; __device__ __forceinline__ unsigned pk2(float lo, float hi) { return pg8::cvt_pk_bf16(lo, hi); }
; __device__ __forceinline__ float siluf_(float x) { return x / (1.f + __expf(-x)); }
; __device__ __forceinline__ void post_phase(const Args& a, int l, int nrows) {
;     ...
;         for (int k = 0; k < 2; ++k) { const int ch = 8 * lane + 512 * k; const float dd = dssd[ch >> 6];
;             const u32x4 zw = *(const u32x4*)(P + (size_t)row * NINP + ZOFF + ch); float z[8]; unpack8(zw, z);
;             float yf[8], yb[8]; unpack8(*(const u32x4*)(yssd + (size_t)row * 1024 + ch), yf); unpack8(*(const u32x4*)(yssd + ((size_t)MROWS + row) * 1024 + ch), yb);
; #pragma unroll
;             for (int q = 0; q < 2; ++q) { const f32x4 xv = *(const f32x4*)(xbc + (size_t)row * 1536 + ch + 4 * q);
; #pragma unroll
;                 for (int j = 0; j < 4; ++j) { const float y = (yf[4 * q + j] + yb[4 * q + j] + dd * xv[j]) * siluf_(z[4 * q + j]); v[k][4 * q + j] = y; ss += y * y; } } }
;         const float rstd = rsqrtf(wave_sum(ss) * (1.f / 1024.f) + EPS);
; #pragma unroll
;         for (int k = 0; k < 2; ++k) { const int ch = 8 * lane + 512 * k; const f32x4 g0 = *(const f32x4*)(gn + ch), g1 = *(const f32x4*)(gn + ch + 4);
;             u32x4 w; w.x = pk2(v[k][0] * rstd * g0[0], v[k][1] * rstd * g0[1]); w.y = pk2(v[k][2] * rstd * g0[2], v[k][3] * rstd * g0[3]);
;             w.z = pk2(v[k][4] * rstd * g1[0], v[k][5] * rstd * g1[1]); w.w = pk2(v[k][6] * rstd * g1[2], v[k][7] * rstd * g1[3]);
;             *(u32x4*)(yss + (size_t)row * 1024 + ch) = w; }
	v_fmac_f32_e32 v61, v74, v17
	v_fma_f32 v13, -v13, v61, v54
	v_div_fmas_f32 v13, v13, v17, v61
	v_div_fixup_f32 v27, v13, v27, v21
	v_div_scale_f32 v13, s[6:7], v26, v26, v33
	v_rcp_f32_e32 v17, v13
	s_nop 0
	v_fma_f32 v21, -v13, v17, 1.0
	v_fmac_f32_e32 v17, v21, v17
	v_div_scale_f32 v21, vcc, v33, v26, v33
	v_mul_f32_e32 v54, v21, v17
	v_fma_f32 v61, -v13, v54, v21
	v_fmac_f32_e32 v54, v61, v17
	v_fma_f32 v13, -v13, v54, v21
	v_div_fmas_f32 v13, v13, v17, v54
	v_div_fixup_f32 v26, v13, v26, v33
	v_lshlrev_b32_e32 v33, 16, v20
	v_and_b32_e32 v54, 0xffff0000, v20
	v_lshlrev_b32_e32 v20, 16, v16
	v_and_b32_e32 v21, 0xffff0000, v16
	v_lshlrev_b32_e32 v16, 16, v12
	v_and_b32_e32 v17, 0xffff0000, v12
	v_pk_add_f32 v[16:17], v[20:21], v[16:17]
	v_mul_f32_e32 v12, 0xbfb8aa3b, v33
	v_pk_fma_f32 v[16:17], v[0:1], v[24:25], v[16:17] op_sel_hi:[0,1,1]
	v_mul_f32_e32 v0, 0xbfb8aa3b, v54
	v_exp_f32_e32 v12, v12
	v_exp_f32_e32 v13, v0
	v_pk_mul_f32 v[18:19], v[18:19], v[26:27]
	v_pk_add_f32 v[12:13], v[12:13], 1.0 op_sel_hi:[1,0]
	s_nop 0
	v_div_scale_f32 v0, s[6:7], v13, v13, v54
	v_rcp_f32_e32 v20, v0
	v_pk_mul_f32 v[26:27], v[18:19], v[18:19]
	v_fma_f32 v21, -v0, v20, 1.0
	v_fmac_f32_e32 v20, v21, v20
	v_div_scale_f32 v21, vcc, v54, v13, v54
	v_mul_f32_e32 v24, v21, v20
	v_fma_f32 v25, -v0, v24, v21
	v_fmac_f32_e32 v24, v25, v20
	v_fma_f32 v0, -v0, v24, v21
	v_div_fmas_f32 v0, v0, v20, v24
	v_div_fixup_f32 v13, v0, v13, v54
	v_div_scale_f32 v0, s[6:7], v12, v12, v33
	v_rcp_f32_e32 v20, v0
	s_mov_b32 s6, 0x1ae00000
	v_fma_f32 v21, -v0, v20, 1.0
	v_fmac_f32_e32 v20, v21, v20
	v_div_scale_f32 v21, vcc, v33, v12, v33
	v_mul_f32_e32 v24, v21, v20
	v_fma_f32 v25, -v0, v24, v21
	v_fmac_f32_e32 v24, v25, v20
	v_fma_f32 v0, -v0, v24, v21
	v_div_fmas_f32 v0, v0, v20, v24
	v_div_fixup_f32 v12, v0, v12, v33
	v_add_f32_e32 v0, v66, v67
	v_add_f32_e32 v0, v72, v0
	v_add_f32_e32 v0, v73, v0
	v_add_f32_e32 v0, v64, v0
	v_add_f32_e32 v0, v65, v0
	v_pk_mul_f32 v[12:13], v[16:17], v[12:13]
	v_add_f32_e32 v0, v2, v0
	v_pk_mul_f32 v[16:17], v[12:13], v[12:13]
	v_add_f32_e32 v0, v3, v0
	v_add_f32_e32 v0, v16, v0
	v_add_f32_e32 v0, v17, v0
	v_add_f32_e32 v0, v26, v0
	v_add_f32_e32 v0, v27, v0
	v_add_f32_e32 v0, v22, v0
	v_add_f32_e32 v0, v23, v0
	v_add_f32_e32 v0, v70, v0
	v_add_f32_e32 v0, v71, v0
	ds_bpermute_b32 v2, v55, v0
	s_waitcnt lgkmcnt(0)
	v_add_f32_e32 v0, v0, v2
	ds_bpermute_b32 v2, v56, v0
	s_waitcnt lgkmcnt(0)
	v_add_f32_e32 v0, v0, v2
	ds_bpermute_b32 v2, v57, v0
	s_waitcnt lgkmcnt(0)
	v_add_f32_e32 v0, v0, v2
	ds_bpermute_b32 v2, v58, v0
	s_waitcnt lgkmcnt(0)
	v_add_f32_e32 v0, v0, v2
	ds_bpermute_b32 v2, v59, v0
	s_waitcnt lgkmcnt(0)
	v_add_f32_e32 v0, v0, v2
	ds_bpermute_b32 v2, v60, v0
	s_waitcnt lgkmcnt(0)
	v_add_f32_e32 v0, v0, v2
	v_fmamk_f32 v0, v0, 0x3a800000, v197
	v_cmp_gt_f32_e32 vcc, s69, v0
	v_mul_f32_e32 v2, 0x4b800000, v0
	s_nop 0
	v_cndmask_b32_e32 v0, v0, v2, vcc
	v_rsq_f32_e32 v0, v0
	s_nop 0
	v_mul_f32_e32 v2, 0x45800000, v0
	v_cndmask_b32_e32 v0, v0, v2, vcc
	v_pk_mul_f32 v[2:3], v[62:63], v[0:1] op_sel_hi:[1,0]
	v_pk_mul_f32 v[12:13], v[12:13], v[0:1] op_sel_hi:[1,0]
	s_waitcnt vmcnt(12)
	v_pk_mul_f32 v[2:3], v[8:9], v[2:3]
	v_pk_mul_f32 v[8:9], v[68:69], v[0:1] op_sel_hi:[1,0]
	v_cvt_pk_bf16_f32 v2, v2, v3
	v_pk_mul_f32 v[8:9], v[10:11], v[8:9]
	v_add_co_u32_e32 v10, vcc, s6, v50
	v_cvt_pk_bf16_f32 v3, v8, v9
	v_pk_mul_f32 v[8:9], v[30:31], v[0:1] op_sel_hi:[1,0]
	v_addc_co_u32_e32 v11, vcc, 0, v51, vcc
	v_pk_mul_f32 v[4:5], v[4:5], v[8:9]
	v_pk_mul_f32 v[8:9], v[52:53], v[0:1] op_sel_hi:[1,0]
	v_cvt_pk_bf16_f32 v4, v4, v5
	v_pk_mul_f32 v[6:7], v[6:7], v[8:9]
	s_mov_b32 s6, 0x8d02000
	v_cvt_pk_bf16_f32 v5, v6, v7
	global_store_dwordx4 v[10:11], v[2:5], off
	s_nop 0
	s_waitcnt vmcnt(11)
	v_pk_mul_f32 v[6:7], v[92:93], v[12:13]
	v_pk_mul_f32 v[12:13], v[18:19], v[0:1] op_sel_hi:[1,0]
	v_cvt_pk_bf16_f32 v6, v6, v7
	v_pk_mul_f32 v[8:9], v[94:95], v[12:13]
	s_nop 0
	v_cvt_pk_bf16_f32 v7, v8, v9
	v_pk_mul_f32 v[8:9], v[14:15], v[0:1] op_sel_hi:[1,0]
	s_nop 0
	v_pk_mul_f32 v[2:3], v[88:89], v[8:9]
	s_nop 0
	v_cvt_pk_bf16_f32 v8, v2, v3
	v_pk_mul_f32 v[2:3], v[28:29], v[0:1] op_sel_hi:[1,0]
	s_nop 0
	v_pk_mul_f32 v[2:3], v[90:91], v[2:3]
	s_nop 0
	v_cvt_pk_bf16_f32 v9, v2, v3
	v_add_co_u32_e32 v2, vcc, s6, v48
	global_store_dwordx4 v[10:11], v[6:9], off offset:1024
	s_nop 0
	v_addc_co_u32_e32 v3, vcc, 0, v49, vcc
	s_mov_b32 s6, 0x27e00000
	v_add_co_u32_e32 v2, vcc, s6, v50
	s_mov_b32 s6, 0x28f00000
	s_nop 0
	v_addc_co_u32_e32 v3, vcc, 0, v51, vcc
	v_add_co_u32_e32 v4, vcc, s6, v50
	s_waitcnt vmcnt(11)
	v_lshlrev_b32_e32 v26, 16, v96
	v_addc_co_u32_e32 v5, vcc, 0, v51, vcc
	v_and_b32_e32 v27, 0xffff0000, v96
	s_waitcnt vmcnt(10)
	v_lshlrev_b32_e32 v28, 16, v100
	v_and_b32_e32 v29, 0xffff0000, v100
	s_waitcnt vmcnt(9)
	v_lshlrev_b32_e32 v30, 16, v104
	v_and_b32_e32 v31, 0xffff0000, v104
	v_pk_add_f32 v[28:29], v[28:29], v[30:31]
	s_waitcnt vmcnt(7)
; __device__ __forceinline__ float gelu_tanh(float x) { const float t = 0.7978845608028654f * (x + 0.044715f * x * x * x); const float e = __expf(2.f * t); const float th = 1.f - 2.f / (e + 1.f); return 0.5f * x * (1.f + th); }
; __device__ __forceinline__ void post_phase(const Args& a, int l, int nrows) {
;     ...
;         for (int k = 0; k < 2; ++k) { const int ch = 8 * lane + 512 * k;
;             const u32x4 uw = *(const u32x4*)(P + (size_t)row * NINP + UOFF + ch); float uu[8]; unpack8(uw, uu); float o[8];
;             float yf[8], yb[8]; unpack8(*(const u32x4*)(ys5 + (size_t)row * 1024 + ch), yf); unpack8(*(const u32x4*)(ys5 + ((size_t)MROWS + row) * 1024 + ch), yb);
; #pragma unroll
;             for (int q = 0; q < 2; ++q) { const f32x4 dv = *(const f32x4*)(ds5 + ch + 4 * q);
; #pragma unroll
;                 for (int j = 0; j < 4; ++j) o[4 * q + j] = gelu_tanh(yf[4 * q + j] + yb[4 * q + j] + dv[j] * uu[4 * q + j]); }
	v_pk_fma_f32 v[22:23], v[112:113], v[26:27], v[28:29]
	s_nop 0
	v_mul_f32_e32 v0, 0x3d372713, v22
	v_mul_f32_e32 v0, v22, v0
	v_fma_f32 v0, v22, v0, v22
	v_mul_f32_e32 v0, 0x3f4c422a, v0
	v_add_f32_e32 v0, v0, v0
	v_mul_f32_e32 v0, 0x3fb8aa3b, v0
	v_exp_f32_e32 v26, v0
	v_mul_f32_e32 v0, 0x3d372713, v23
	v_mul_f32_e32 v0, v23, v0
	v_fma_f32 v0, v23, v0, v23
	v_mul_f32_e32 v0, 0x3f4c422a, v0
	v_add_f32_e32 v0, v0, v0
	v_mul_f32_e32 v0, 0x3fb8aa3b, v0
	v_exp_f32_e32 v27, v0
	v_pk_mul_f32 v[22:23], v[22:23], 0.5 op_sel_hi:[1,0]
	v_pk_add_f32 v[26:27], v[26:27], 1.0 op_sel_hi:[1,0]
	s_nop 0
	v_div_scale_f32 v0, s[6:7], v27, v27, 2.0
	v_rcp_f32_e32 v6, v0
	s_nop 0
	v_fma_f32 v10, -v0, v6, 1.0
	v_fmac_f32_e32 v6, v10, v6
	v_div_scale_f32 v10, vcc, 2.0, v27, 2.0
	v_mul_f32_e32 v14, v10, v6
	v_fma_f32 v28, -v0, v14, v10
	v_fmac_f32_e32 v14, v28, v6
	v_fma_f32 v0, -v0, v14, v10
	v_div_fmas_f32 v0, v0, v6, v14
	v_div_fixup_f32 v27, v0, v27, 2.0
	v_div_scale_f32 v0, s[6:7], v26, v26, 2.0
	v_rcp_f32_e32 v6, v0
	s_nop 0
	v_fma_f32 v10, -v0, v6, 1.0
	v_fmac_f32_e32 v6, v10, v6
	v_div_scale_f32 v10, vcc, 2.0, v26, 2.0
	v_mul_f32_e32 v14, v10, v6
	v_fma_f32 v28, -v0, v14, v10
	v_fmac_f32_e32 v14, v28, v6
	v_fma_f32 v0, -v0, v14, v10
	v_div_fmas_f32 v0, v0, v6, v14
	v_lshlrev_b32_e32 v10, 16, v101
	v_and_b32_e32 v11, 0xffff0000, v101
	v_lshlrev_b32_e32 v14, 16, v105
	v_and_b32_e32 v15, 0xffff0000, v105
	v_lshlrev_b32_e32 v6, 16, v97
	v_and_b32_e32 v7, 0xffff0000, v97
	v_pk_add_f32 v[10:11], v[10:11], v[14:15]
	v_div_fixup_f32 v26, v0, v26, 2.0
	v_pk_fma_f32 v[6:7], v[114:115], v[6:7], v[10:11]
	v_pk_add_f32 v[26:27], v[26:27], 1.0 op_sel_hi:[1,0] neg_lo:[1,0] neg_hi:[1,0]
	v_mul_f32_e32 v0, 0x3d372713, v6
	v_mul_f32_e32 v0, v6, v0
	v_fma_f32 v0, v6, v0, v6
	v_mul_f32_e32 v0, 0x3f4c422a, v0
	v_add_f32_e32 v0, v0, v0
	v_mul_f32_e32 v0, 0x3fb8aa3b, v0
	v_exp_f32_e32 v10, v0
	v_mul_f32_e32 v0, 0x3d372713, v7
	v_mul_f32_e32 v0, v7, v0
	v_fma_f32 v0, v7, v0, v7
	v_mul_f32_e32 v0, 0x3f4c422a, v0
	v_add_f32_e32 v0, v0, v0
	v_mul_f32_e32 v0, 0x3fb8aa3b, v0
	v_exp_f32_e32 v11, v0
	v_pk_mul_f32 v[6:7], v[6:7], 0.5 op_sel_hi:[1,0]
	v_pk_add_f32 v[26:27], v[26:27], 1.0 op_sel_hi:[1,0]
	v_pk_add_f32 v[10:11], v[10:11], 1.0 op_sel_hi:[1,0]
	s_nop 0
	v_div_scale_f32 v0, s[6:7], v11, v11, 2.0
	v_rcp_f32_e32 v14, v0
	v_pk_mul_f32 v[22:23], v[22:23], v[26:27]
	v_fma_f32 v15, -v0, v14, 1.0
	v_fmac_f32_e32 v14, v15, v14
	v_div_scale_f32 v15, vcc, 2.0, v11, 2.0
	v_mul_f32_e32 v24, v15, v14
	v_fma_f32 v25, -v0, v24, v15
	v_fmac_f32_e32 v24, v25, v14
	v_fma_f32 v0, -v0, v24, v15
	v_div_fmas_f32 v0, v0, v14, v24
	v_div_fixup_f32 v11, v0, v11, 2.0
	v_div_scale_f32 v0, s[6:7], v10, v10, 2.0
	v_rcp_f32_e32 v14, v0
	s_nop 0
	v_fma_f32 v15, -v0, v14, 1.0
	v_fmac_f32_e32 v14, v15, v14
	v_div_scale_f32 v15, vcc, 2.0, v10, 2.0
	v_mul_f32_e32 v24, v15, v14
	v_fma_f32 v25, -v0, v24, v15
	v_fmac_f32_e32 v24, v25, v14
	v_fma_f32 v0, -v0, v24, v15
	v_div_fmas_f32 v0, v0, v14, v24
	v_div_fixup_f32 v10, v0, v10, 2.0
	v_pk_add_f32 v[10:11], v[10:11], 1.0 op_sel_hi:[1,0] neg_lo:[1,0] neg_hi:[1,0]
	v_lshlrev_b32_e32 v14, 16, v102
	v_pk_add_f32 v[10:11], v[10:11], 1.0 op_sel_hi:[1,0]
	v_and_b32_e32 v15, 0xffff0000, v102
	v_lshlrev_b32_e32 v24, 16, v106
	v_and_b32_e32 v25, 0xffff0000, v106
	v_pk_mul_f32 v[10:11], v[6:7], v[10:11]
	v_lshlrev_b32_e32 v6, 16, v98
	v_and_b32_e32 v7, 0xffff0000, v98
	v_pk_add_f32 v[14:15], v[14:15], v[24:25]
	s_nop 0
	v_pk_fma_f32 v[6:7], v[108:109], v[6:7], v[14:15]
	s_nop 0
	v_mul_f32_e32 v0, 0x3d372713, v6
	v_mul_f32_e32 v0, v6, v0
	v_fma_f32 v0, v6, v0, v6
	v_mul_f32_e32 v0, 0x3f4c422a, v0
	v_add_f32_e32 v0, v0, v0
	v_mul_f32_e32 v0, 0x3fb8aa3b, v0
	v_exp_f32_e32 v14, v0
	v_mul_f32_e32 v0, 0x3d372713, v7
	v_mul_f32_e32 v0, v7, v0
	v_fma_f32 v0, v7, v0, v7
	v_mul_f32_e32 v0, 0x3f4c422a, v0
	v_add_f32_e32 v0, v0, v0
	v_mul_f32_e32 v0, 0x3fb8aa3b, v0
	v_exp_f32_e32 v15, v0
	v_pk_mul_f32 v[6:7], v[6:7], 0.5 op_sel_hi:[1,0]
	v_pk_add_f32 v[14:15], v[14:15], 1.0 op_sel_hi:[1,0]
	s_nop 0
	v_div_scale_f32 v0, s[6:7], v15, v15, 2.0
	v_rcp_f32_e32 v8, v0
	s_nop 0
	v_fma_f32 v12, -v0, v8, 1.0
	v_fmac_f32_e32 v8, v12, v8
	v_div_scale_f32 v12, vcc, 2.0, v15, 2.0
	v_mul_f32_e32 v16, v12, v8
	v_fma_f32 v18, -v0, v16, v12
	v_fmac_f32_e32 v16, v18, v8
	v_fma_f32 v0, -v0, v16, v12
	v_div_fmas_f32 v0, v0, v8, v16
	v_div_fixup_f32 v15, v0, v15, 2.0
	v_div_scale_f32 v0, s[6:7], v14, v14, 2.0
	v_rcp_f32_e32 v8, v0
	s_nop 0
	v_fma_f32 v12, -v0, v8, 1.0
	v_fmac_f32_e32 v8, v12, v8
	v_div_scale_f32 v12, vcc, 2.0, v14, 2.0
	v_mul_f32_e32 v16, v12, v8
	v_fma_f32 v18, -v0, v16, v12
	v_fmac_f32_e32 v16, v18, v8
	v_fma_f32 v0, -v0, v16, v12
	v_div_fmas_f32 v0, v0, v8, v16
	v_div_fixup_f32 v14, v0, v14, 2.0
	v_pk_add_f32 v[14:15], v[14:15], 1.0 op_sel_hi:[1,0] neg_lo:[1,0] neg_hi:[1,0]
	v_lshlrev_b32_e32 v8, 16, v103
	v_pk_add_f32 v[14:15], v[14:15], 1.0 op_sel_hi:[1,0]
	v_lshlrev_b32_e32 v12, 16, v107
	v_pk_mul_f32 v[14:15], v[6:7], v[14:15]
	v_lshlrev_b32_e32 v6, 16, v99
	v_and_b32_e32 v7, 0xffff0000, v99
	v_and_b32_e32 v9, 0xffff0000, v103
	v_and_b32_e32 v13, 0xffff0000, v107
	v_pk_add_f32 v[8:9], v[8:9], v[12:13]
	s_nop 0
	v_pk_fma_f32 v[6:7], v[110:111], v[6:7], v[8:9]
	s_nop 0
	v_mul_f32_e32 v0, 0x3d372713, v6
	v_mul_f32_e32 v0, v6, v0
	v_fma_f32 v0, v6, v0, v6
	v_mul_f32_e32 v0, 0x3f4c422a, v0
	v_add_f32_e32 v0, v0, v0
	v_mul_f32_e32 v0, 0x3fb8aa3b, v0
	v_exp_f32_e32 v8, v0
	v_mul_f32_e32 v0, 0x3d372713, v7
	v_mul_f32_e32 v0, v7, v0
	v_fma_f32 v0, v7, v0, v7
	v_mul_f32_e32 v0, 0x3f4c422a, v0
	v_add_f32_e32 v0, v0, v0
	v_mul_f32_e32 v0, 0x3fb8aa3b, v0
	v_exp_f32_e32 v9, v0
; __device__ __forceinline__ unsigned pk2(float lo, float hi) { return pg8::cvt_pk_bf16(lo, hi); }
; __device__ __forceinline__ float gelu_tanh(float x) { const float t = 0.7978845608028654f * (x + 0.044715f * x * x * x); const float e = __expf(2.f * t); const float th = 1.f - 2.f / (e + 1.f); return 0.5f * x * (1.f + th); }
; __device__ __forceinline__ void post_phase(const Args& a, int l, int nrows) {
;     ...
;         for (int k = 0; k < 2; ++k) { const int ch = 8 * lane + 512 * k;
;             const u32x4 uw = *(const u32x4*)(P + (size_t)row * NINP + UOFF + ch); float uu[8]; unpack8(uw, uu); float o[8];
;             float yf[8], yb[8]; unpack8(*(const u32x4*)(ys5 + (size_t)row * 1024 + ch), yf); unpack8(*(const u32x4*)(ys5 + ((size_t)MROWS + row) * 1024 + ch), yb);
; #pragma unroll
;             for (int q = 0; q < 2; ++q) { const f32x4 dv = *(const f32x4*)(ds5 + ch + 4 * q);
; #pragma unroll
;                 for (int j = 0; j < 4; ++j) o[4 * q + j] = gelu_tanh(yf[4 * q + j] + yb[4 * q + j] + dv[j] * uu[4 * q + j]); }
;             u32x4 w; w.x = pk2(o[0], o[1]); w.y = pk2(o[2], o[3]); w.z = pk2(o[4], o[5]); w.w = pk2(o[6], o[7]);
;             *(u32x4*)(s5g + (size_t)row * 1024 + ch) = w; }
	v_pk_mul_f32 v[6:7], v[6:7], 0.5 op_sel_hi:[1,0]
	v_pk_add_f32 v[8:9], v[8:9], 1.0 op_sel_hi:[1,0]
	s_nop 0
	v_div_scale_f32 v0, s[6:7], v9, v9, 2.0
	v_rcp_f32_e32 v12, v0
	s_nop 0
	v_fma_f32 v13, -v0, v12, 1.0
	v_fmac_f32_e32 v12, v13, v12
	v_div_scale_f32 v13, vcc, 2.0, v9, 2.0
	v_mul_f32_e32 v16, v13, v12
	v_fma_f32 v17, -v0, v16, v13
	v_fmac_f32_e32 v16, v17, v12
	v_fma_f32 v0, -v0, v16, v13
	v_div_fmas_f32 v0, v0, v12, v16
	v_div_fixup_f32 v9, v0, v9, 2.0
	v_div_scale_f32 v0, s[6:7], v8, v8, 2.0
	v_rcp_f32_e32 v12, v0
	s_mov_b32 s6, 0x18c00000
	v_fma_f32 v13, -v0, v12, 1.0
	v_fmac_f32_e32 v12, v13, v12
	v_div_scale_f32 v13, vcc, 2.0, v8, 2.0
	v_mul_f32_e32 v16, v13, v12
	v_fma_f32 v17, -v0, v16, v13
	v_fmac_f32_e32 v16, v17, v12
	v_fma_f32 v0, -v0, v16, v13
	v_div_fmas_f32 v0, v0, v12, v16
	v_div_fixup_f32 v8, v0, v8, 2.0
	v_pk_add_f32 v[8:9], v[8:9], 1.0 op_sel_hi:[1,0] neg_lo:[1,0] neg_hi:[1,0]
	s_nop 0
	v_pk_add_f32 v[8:9], v[8:9], 1.0 op_sel_hi:[1,0]
	s_nop 0
	v_pk_mul_f32 v[12:13], v[6:7], v[8:9]
	v_cvt_pk_bf16_f32 v6, v22, v23
	v_add_co_u32_e32 v22, vcc, s6, v50
	v_cvt_pk_bf16_f32 v7, v10, v11
	v_cvt_pk_bf16_f32 v8, v14, v15
	v_cvt_pk_bf16_f32 v9, v12, v13
	v_addc_co_u32_e32 v23, vcc, 0, v51, vcc
	s_mov_b32 s6, 0x8d03000
	global_store_dwordx4 v[22:23], v[6:9], off
	s_nop 1
	v_add_co_u32_e32 v6, vcc, s6, v48
	s_nop 1
	v_addc_co_u32_e32 v7, vcc, 0, v49, vcc
	s_nop 0
	s_nop 0
	s_nop 0
	s_waitcnt vmcnt(7)
	v_lshlrev_b32_e32 v24, 16, v116
	s_waitcnt vmcnt(6)
	v_lshlrev_b32_e32 v26, 16, v120
	v_and_b32_e32 v27, 0xffff0000, v120
	s_waitcnt vmcnt(5)
	v_lshlrev_b32_e32 v28, 16, v124
	v_and_b32_e32 v29, 0xffff0000, v124
	v_and_b32_e32 v25, 0xffff0000, v116
	v_pk_add_f32 v[26:27], v[26:27], v[28:29]
	s_waitcnt vmcnt(3)
; __device__ __forceinline__ unsigned pk2(float lo, float hi) { return pg8::cvt_pk_bf16(lo, hi); }
; __device__ __forceinline__ float gelu_tanh(float x) { const float t = 0.7978845608028654f * (x + 0.044715f * x * x * x); const float e = __expf(2.f * t); const float th = 1.f - 2.f / (e + 1.f); return 0.5f * x * (1.f + th); }
; __device__ __forceinline__ void post_phase(const Args& a, int l, int nrows) {
;     ...
;         for (int k = 0; k < 2; ++k) { const int ch = 8 * lane + 512 * k;
;             const u32x4 uw = *(const u32x4*)(P + (size_t)row * NINP + UOFF + ch); float uu[8]; unpack8(uw, uu); float o[8];
;             float yf[8], yb[8]; unpack8(*(const u32x4*)(ys5 + (size_t)row * 1024 + ch), yf); unpack8(*(const u32x4*)(ys5 + ((size_t)MROWS + row) * 1024 + ch), yb);
; #pragma unroll
;             for (int q = 0; q < 2; ++q) { const f32x4 dv = *(const f32x4*)(ds5 + ch + 4 * q);
; #pragma unroll
;                 for (int j = 0; j < 4; ++j) o[4 * q + j] = gelu_tanh(yf[4 * q + j] + yb[4 * q + j] + dv[j] * uu[4 * q + j]); }
;             u32x4 w; w.x = pk2(o[0], o[1]); w.y = pk2(o[2], o[3]); w.z = pk2(o[4], o[5]); w.w = pk2(o[6], o[7]);
;             *(u32x4*)(s5g + (size_t)row * 1024 + ch) = w; }
;     }
	v_pk_fma_f32 v[18:19], v[132:133], v[24:25], v[26:27]
	s_nop 0
	v_mul_f32_e32 v0, 0x3d372713, v18
	v_mul_f32_e32 v0, v18, v0
	v_fma_f32 v0, v18, v0, v18
	v_mul_f32_e32 v0, 0x3f4c422a, v0
	v_add_f32_e32 v0, v0, v0
	v_mul_f32_e32 v0, 0x3fb8aa3b, v0
	v_exp_f32_e32 v24, v0
	v_mul_f32_e32 v0, 0x3d372713, v19
	v_mul_f32_e32 v0, v19, v0
	v_fma_f32 v0, v19, v0, v19
	v_mul_f32_e32 v0, 0x3f4c422a, v0
	v_add_f32_e32 v0, v0, v0
	v_mul_f32_e32 v0, 0x3fb8aa3b, v0
	v_exp_f32_e32 v25, v0
	v_pk_mul_f32 v[18:19], v[18:19], 0.5 op_sel_hi:[1,0]
	v_pk_add_f32 v[24:25], v[24:25], 1.0 op_sel_hi:[1,0]
	s_nop 0
	v_div_scale_f32 v0, s[6:7], v25, v25, 2.0
	v_rcp_f32_e32 v2, v0
	s_nop 0
	v_fma_f32 v6, -v0, v2, 1.0
	v_fmac_f32_e32 v2, v6, v2
	v_div_scale_f32 v6, vcc, 2.0, v25, 2.0
	v_mul_f32_e32 v10, v6, v2
	v_fma_f32 v26, -v0, v10, v6
	v_fmac_f32_e32 v10, v26, v2
	v_fma_f32 v0, -v0, v10, v6
	v_div_fmas_f32 v0, v0, v2, v10
	v_div_fixup_f32 v25, v0, v25, 2.0
	v_div_scale_f32 v0, s[6:7], v24, v24, 2.0
	v_rcp_f32_e32 v2, v0
	s_nop 0
	v_fma_f32 v6, -v0, v2, 1.0
	v_fmac_f32_e32 v2, v6, v2
	v_div_scale_f32 v6, vcc, 2.0, v24, 2.0
	v_mul_f32_e32 v10, v6, v2
	v_fma_f32 v26, -v0, v10, v6
	v_fmac_f32_e32 v10, v26, v2
	v_fma_f32 v0, -v0, v10, v6
	v_div_fmas_f32 v0, v0, v2, v10
	v_lshlrev_b32_e32 v10, 16, v121
	v_and_b32_e32 v11, 0xffff0000, v121
	v_lshlrev_b32_e32 v2, 16, v125
	v_and_b32_e32 v3, 0xffff0000, v125
	v_lshlrev_b32_e32 v6, 16, v117
	v_and_b32_e32 v7, 0xffff0000, v117
	v_pk_add_f32 v[2:3], v[10:11], v[2:3]
	v_div_fixup_f32 v24, v0, v24, 2.0
	v_pk_fma_f32 v[2:3], v[134:135], v[6:7], v[2:3]
	v_pk_add_f32 v[24:25], v[24:25], 1.0 op_sel_hi:[1,0] neg_lo:[1,0] neg_hi:[1,0]
	v_mul_f32_e32 v0, 0x3d372713, v2
	v_mul_f32_e32 v0, v2, v0
	v_fma_f32 v0, v2, v0, v2
	v_mul_f32_e32 v0, 0x3f4c422a, v0
	v_add_f32_e32 v0, v0, v0
	v_mul_f32_e32 v0, 0x3fb8aa3b, v0
	v_exp_f32_e32 v6, v0
	v_mul_f32_e32 v0, 0x3d372713, v3
	v_mul_f32_e32 v0, v3, v0
	v_fma_f32 v0, v3, v0, v3
	v_mul_f32_e32 v0, 0x3f4c422a, v0
	v_add_f32_e32 v0, v0, v0
	v_mul_f32_e32 v0, 0x3fb8aa3b, v0
	v_exp_f32_e32 v7, v0
	v_pk_mul_f32 v[2:3], v[2:3], 0.5 op_sel_hi:[1,0]
	v_pk_add_f32 v[24:25], v[24:25], 1.0 op_sel_hi:[1,0]
	v_pk_add_f32 v[6:7], v[6:7], 1.0 op_sel_hi:[1,0]
	s_nop 0
	v_div_scale_f32 v0, s[6:7], v7, v7, 2.0
	v_rcp_f32_e32 v10, v0
	v_pk_mul_f32 v[18:19], v[18:19], v[24:25]
	v_fma_f32 v11, -v0, v10, 1.0
	v_fmac_f32_e32 v10, v11, v10
	v_div_scale_f32 v11, vcc, 2.0, v7, 2.0
	v_mul_f32_e32 v20, v11, v10
	v_fma_f32 v21, -v0, v20, v11
	v_fmac_f32_e32 v20, v21, v10
	v_fma_f32 v0, -v0, v20, v11
	v_div_fmas_f32 v0, v0, v10, v20
	v_div_fixup_f32 v7, v0, v7, 2.0
	v_div_scale_f32 v0, s[6:7], v6, v6, 2.0
	v_rcp_f32_e32 v10, v0
	s_nop 0
	v_fma_f32 v11, -v0, v10, 1.0
	v_fmac_f32_e32 v10, v11, v10
	v_div_scale_f32 v11, vcc, 2.0, v6, 2.0
	v_mul_f32_e32 v20, v11, v10
	v_fma_f32 v21, -v0, v20, v11
	v_fmac_f32_e32 v20, v21, v10
	v_fma_f32 v0, -v0, v20, v11
	v_div_fmas_f32 v0, v0, v10, v20
	v_div_fixup_f32 v6, v0, v6, 2.0
	v_pk_add_f32 v[6:7], v[6:7], 1.0 op_sel_hi:[1,0] neg_lo:[1,0] neg_hi:[1,0]
	v_lshlrev_b32_e32 v10, 16, v122
	v_pk_add_f32 v[6:7], v[6:7], 1.0 op_sel_hi:[1,0]
	v_and_b32_e32 v11, 0xffff0000, v122
	v_lshlrev_b32_e32 v20, 16, v126
	v_and_b32_e32 v21, 0xffff0000, v126
	v_pk_mul_f32 v[6:7], v[2:3], v[6:7]
	v_lshlrev_b32_e32 v2, 16, v118
	v_and_b32_e32 v3, 0xffff0000, v118
	v_pk_add_f32 v[10:11], v[10:11], v[20:21]
	s_nop 0
	v_pk_fma_f32 v[2:3], v[128:129], v[2:3], v[10:11]
	s_nop 0
	v_mul_f32_e32 v0, 0x3d372713, v2
	v_mul_f32_e32 v0, v2, v0
	v_fma_f32 v0, v2, v0, v2
	v_mul_f32_e32 v0, 0x3f4c422a, v0
	v_add_f32_e32 v0, v0, v0
	v_mul_f32_e32 v0, 0x3fb8aa3b, v0
	v_exp_f32_e32 v10, v0
	v_mul_f32_e32 v0, 0x3d372713, v3
	v_mul_f32_e32 v0, v3, v0
	v_fma_f32 v0, v3, v0, v3
	v_mul_f32_e32 v0, 0x3f4c422a, v0
	v_add_f32_e32 v0, v0, v0
	v_mul_f32_e32 v0, 0x3fb8aa3b, v0
	v_exp_f32_e32 v11, v0
	v_pk_mul_f32 v[2:3], v[2:3], 0.5 op_sel_hi:[1,0]
	v_pk_add_f32 v[10:11], v[10:11], 1.0 op_sel_hi:[1,0]
	s_nop 0
	v_div_scale_f32 v0, s[6:7], v11, v11, 2.0
	v_rcp_f32_e32 v4, v0
	s_nop 0
	v_fma_f32 v8, -v0, v4, 1.0
	v_fmac_f32_e32 v4, v8, v4
	v_div_scale_f32 v8, vcc, 2.0, v11, 2.0
	v_mul_f32_e32 v12, v8, v4
	v_fma_f32 v14, -v0, v12, v8
	v_fmac_f32_e32 v12, v14, v4
	v_fma_f32 v0, -v0, v12, v8
	v_div_fmas_f32 v0, v0, v4, v12
	v_div_fixup_f32 v11, v0, v11, 2.0
	v_div_scale_f32 v0, s[6:7], v10, v10, 2.0
	v_rcp_f32_e32 v4, v0
	s_nop 0
	v_fma_f32 v8, -v0, v4, 1.0
	v_fmac_f32_e32 v4, v8, v4
	v_div_scale_f32 v8, vcc, 2.0, v10, 2.0
	v_mul_f32_e32 v12, v8, v4
	v_fma_f32 v14, -v0, v12, v8
	v_fmac_f32_e32 v12, v14, v4
	v_fma_f32 v0, -v0, v12, v8
	v_div_fmas_f32 v0, v0, v4, v12
	v_div_fixup_f32 v10, v0, v10, 2.0
	v_pk_add_f32 v[10:11], v[10:11], 1.0 op_sel_hi:[1,0] neg_lo:[1,0] neg_hi:[1,0]
	v_lshlrev_b32_e32 v8, 16, v123
	v_pk_add_f32 v[10:11], v[10:11], 1.0 op_sel_hi:[1,0]
	v_lshlrev_b32_e32 v4, 16, v127
	v_pk_mul_f32 v[10:11], v[2:3], v[10:11]
	v_lshlrev_b32_e32 v2, 16, v119
	v_and_b32_e32 v3, 0xffff0000, v119
	v_and_b32_e32 v9, 0xffff0000, v123
	v_and_b32_e32 v5, 0xffff0000, v127
	v_pk_add_f32 v[4:5], v[8:9], v[4:5]
	s_nop 0
	v_pk_fma_f32 v[2:3], v[130:131], v[2:3], v[4:5]
	s_nop 0
	v_mul_f32_e32 v0, 0x3d372713, v2
	v_mul_f32_e32 v0, v2, v0
	v_fma_f32 v0, v2, v0, v2
	v_mul_f32_e32 v0, 0x3f4c422a, v0
	v_add_f32_e32 v0, v0, v0
	v_mul_f32_e32 v0, 0x3fb8aa3b, v0
	v_exp_f32_e32 v4, v0
	v_mul_f32_e32 v0, 0x3d372713, v3
	v_mul_f32_e32 v0, v3, v0
	v_fma_f32 v0, v3, v0, v3
	v_mul_f32_e32 v0, 0x3f4c422a, v0
	v_add_f32_e32 v0, v0, v0
	v_mul_f32_e32 v0, 0x3fb8aa3b, v0
	v_exp_f32_e32 v5, v0
	v_pk_mul_f32 v[2:3], v[2:3], 0.5 op_sel_hi:[1,0]
	v_pk_add_f32 v[4:5], v[4:5], 1.0 op_sel_hi:[1,0]
	s_nop 0
	v_div_scale_f32 v0, s[6:7], v5, v5, 2.0
	v_rcp_f32_e32 v8, v0
	s_nop 0
	v_fma_f32 v9, -v0, v8, 1.0
	v_fmac_f32_e32 v8, v9, v8
	v_div_scale_f32 v9, vcc, 2.0, v5, 2.0
	v_mul_f32_e32 v12, v9, v8
	v_fma_f32 v13, -v0, v12, v9
	v_fmac_f32_e32 v12, v13, v8
	v_fma_f32 v0, -v0, v12, v9
	v_div_fmas_f32 v0, v0, v8, v12
	v_div_fixup_f32 v5, v0, v5, 2.0
	v_div_scale_f32 v0, s[6:7], v4, v4, 2.0
	v_rcp_f32_e32 v8, v0
	s_nop 0
	v_fma_f32 v9, -v0, v8, 1.0
	v_fmac_f32_e32 v8, v9, v8
	v_div_scale_f32 v9, vcc, 2.0, v4, 2.0
	v_mul_f32_e32 v12, v9, v8
	v_fma_f32 v13, -v0, v12, v9
	v_fmac_f32_e32 v12, v13, v8
	v_fma_f32 v0, -v0, v12, v9
	v_div_fmas_f32 v0, v0, v8, v12
	v_div_fixup_f32 v4, v0, v4, 2.0
	v_pk_add_f32 v[4:5], v[4:5], 1.0 op_sel_hi:[1,0] neg_lo:[1,0] neg_hi:[1,0]
	v_cmp_le_i32_e32 vcc, s36, v32
	v_pk_add_f32 v[4:5], v[4:5], 1.0 op_sel_hi:[1,0]
	s_or_b64 s[4:5], vcc, s[4:5]
	v_pk_mul_f32 v[8:9], v[2:3], v[4:5]
	v_cvt_pk_bf16_f32 v2, v18, v19
	v_cvt_pk_bf16_f32 v3, v6, v7
	v_cvt_pk_bf16_f32 v4, v10, v11
	v_cvt_pk_bf16_f32 v5, v8, v9
	global_store_dwordx4 v[22:23], v[2:5], off offset:1024
	s_andn2_b64 exec, exec, s[4:5]
	s_cbranch_execnz .LBB0_622
